# attention: LDS bias/mask table and sub-LN gains built once per phase per CU (head is constant for a CU) instead of once per unit
# speedup vs baseline: 1.0070x; 1.0070x over previous
.LBB0_152:
	v_readlane_b32 s2, v252, 10
	v_mbcnt_lo_u32_b32 v237, -1, 0
	v_mbcnt_hi_u32_b32 v237, -1, v237
	s_nop 1
	v_add_u32_e32 v34, s2, v237
	s_movk_i32 s2, 0x80
	v_readfirstlane_b32 s6, v34
	v_cmp_gt_i32_e32 vcc, s2, v34
	v_readlane_b32 s2, v252, 12
	s_nop 1
	s_cmp_eq_u32 s43, s2
	s_cbranch_scc1 .Ltb_build__u1_a
	s_cmpk_eq_u32 s12, 0x100
	s_cbranch_scc1 .Ltb_u1_a
.Ltb_build__u1_a:
	s_and_saveexec_b64 s[26:27], vcc
	s_cbranch_execz .LBB0_154
	v_readlane_b32 s2, v255, 39
	v_ashrrev_i32_e32 v35, 31, v34
	v_readlane_b32 s3, v255, 40
	v_lshl_add_u32 v0, v34, 2, 0
	v_add_u32_e32 v0, 0x19000, v0
	v_lshl_add_u64 v[2:3], v[34:35], 2, s[2:3]
	global_load_dword v2, v[2:3], off
	s_waitcnt vmcnt(0)
	ds_write_b32 v0, v2

.Ltb_u1_a:
	s_bfe_u32 s28, s43, 0x40004
	v_readlane_b32 s60, v254, 43
	s_lshl_b32 s2, s28, 2
	v_readlane_b32 s62, v254, 45
	v_readlane_b32 s63, v254, 46
	s_add_u32 s38, s62, s2
	s_movk_i32 s2, 0x510
	s_addc_u32 s39, s63, 0
	v_cmp_gt_i32_e32 vcc, s2, v34
	v_readlane_b32 s61, v254, 44
	v_readlane_b32 s64, v254, 47
	v_readlane_b32 s65, v254, 48
	v_readlane_b32 s66, v254, 49
	v_readlane_b32 s67, v254, 50
	v_readlane_b32 s68, v254, 51
	v_readlane_b32 s69, v254, 52
	v_readlane_b32 s70, v254, 53
	v_readlane_b32 s71, v254, 54
	v_readlane_b32 s72, v254, 55
	v_readlane_b32 s73, v254, 56
	v_readlane_b32 s74, v254, 57
	v_readlane_b32 s75, v254, 58
	v_readlane_b32 s2, v252, 12
	s_nop 1
	s_cmp_eq_u32 s43, s2
	s_cbranch_scc1 .Ltb_build__u1_b
	s_cmpk_eq_u32 s12, 0x100
	s_cbranch_scc1 .Ltb_u1_b
.Ltb_build__u1_b:
	s_and_saveexec_b64 s[26:27], vcc
	s_cbranch_execz .LBB0_163
	global_load_dword v2, v1, s[38:39] offset:1984
	v_sub_u32_e32 v3, 0xdf, v34
	v_lshl_add_u32 v4, v34, 2, s33
	s_mov_b64 s[40:41], 0
	v_mov_b32_e32 v5, v34
	s_branch .LBB0_159

.Ltb_u1_b:
	s_ashr_i32 s11, s6, 6
	s_lshl_b32 s10, s43, 4
	s_lshl_b32 s26, s11, 2
	v_bfe_u32 v233, v237, 4, 2
	s_and_b32 s60, s10, 0xfffff000
	v_or_b32_e32 v52, s26, v233
	s_waitcnt vmcnt(0)
	v_add_u32_e32 v2, s60, v52
	v_ashrrev_i32_e32 v3, 31, v2
	v_readlane_b32 s18, v252, 31
	v_bitop3_b32 v0, s26, v237, v233 bitop3:0x36
	v_lshlrev_b64 v[2:3], 12, v[2:3]
	v_readlane_b32 s19, v252, 32
	s_and_b32 s46, s43, 15
	s_lshl_b32 s84, s28, 8
	v_lshl_add_u64 v[2:3], s[18:19], 0, v[2:3]
	v_lshlrev_b32_e32 v0, 4, v0
	s_xor_b32 s17, s46, 31
	s_and_b32 s2, s11, 3
	v_lshl_add_u64 v[2:3], v[2:3], 0, s[84:85]
	v_and_b32_e32 v0, 0xf0, v0
	s_lshl_b32 s27, s11, 3
	v_bfe_u32 v53, v237, 3, 3
	s_lshl_b32 s21, s17, 7
	s_lshl_b32 s22, s2, 5
	s_lshl_b32 s18, s28, 7
	v_lshl_add_u64 v[2:3], v[2:3], 0, v[0:1]
	v_or_b32_e32 v0, s27, v53
	s_or_b32 s20, s22, s21
	v_lshrrev_b32_e32 v54, 1, v0
	v_add_u32_e32 v4, s18, v0
	v_and_b32_e32 v235, 31, v237
	v_xor_b32_e32 v6, v54, v237
	v_ashrrev_i32_e32 v5, 31, v4
	v_readlane_b32 s36, v252, 39
	s_or_b32 s10, s20, s60
	v_lshlrev_b64 v[4:5], 15, v[4:5]
	v_readlane_b32 s37, v252, 40
	v_lshlrev_b32_e32 v0, 4, v6
	v_or_b32_e32 v6, s10, v235
	v_lshl_add_u64 v[4:5], s[36:37], 0, v[4:5]
	v_ashrrev_i32_e32 v7, 31, v6
	v_readlane_b32 s36, v252, 17
	s_ashr_i32 s3, s6, 8
	v_lshlrev_b64 v[6:7], 12, v[6:7]
	v_readlane_b32 s37, v252, 18
	s_ashr_i32 s61, s60, 31
	v_bfe_u32 v234, v237, 5, 1
	v_lshl_add_u64 v[6:7], s[36:37], 0, v[6:7]
	s_lshl_b32 s36, s3, 6
	v_lshl_add_u64 v[4:5], s[60:61], 1, v[4:5]
	v_and_b32_e32 v0, 0x70, v0
	v_lshl_add_u64 v[6:7], v[6:7], 0, s[84:85]
	s_ashr_i32 s37, s36, 31
	v_lshl_add_u64 v[4:5], v[4:5], 0, v[0:1]
	v_lshl_add_u64 v[6:7], s[36:37], 1, v[6:7]
	v_lshlrev_b32_e32 v0, 4, v234
	v_lshl_add_u64 v[6:7], v[6:7], 0, v[0:1]
	global_load_dwordx4 v[146:149], v[6:7], off nt
	global_load_dwordx4 v[150:153], v[6:7], off offset:32 nt
	global_load_dwordx4 v[154:157], v[6:7], off offset:64 nt
	global_load_dwordx4 v[158:161], v[6:7], off offset:96 nt
	s_lshl_b32 s11, s11, 10
	s_add_i32 s11, s11, 0
	s_mov_b32 m0, s11
	s_mov_b64 s[36:37], 0x20000
	global_load_lds_dwordx4 v[2:3], off
	v_lshl_add_u64 v[8:9], v[2:3], 0, s[36:37]
	s_add_i32 m0, s11, 0x2000
	s_mov_b64 s[36:37], 0x40000
	global_load_lds_dwordx4 v[8:9], off
	s_add_i32 m0, s11, 0x4000
	v_lshl_add_u64 v[8:9], v[2:3], 0, s[36:37]
	s_mov_b64 s[36:37], 0x60000
	global_load_lds_dwordx4 v[8:9], off
	v_lshl_add_u64 v[8:9], v[2:3], 0, s[36:37]
	s_add_i32 m0, s11, 0x6000
	s_mov_b64 s[36:37], 0x200000
	global_load_lds_dwordx4 v[8:9], off
	s_add_i32 m0, s11, 0xc000
	v_lshl_add_u64 v[8:9], v[4:5], 0, s[36:37]
	global_load_lds_dwordx4 v[4:5], off
	s_add_i32 m0, s11, 0xe000
	s_mov_b64 s[36:37], 0xa0000
	global_load_lds_dwordx4 v[8:9], off
	s_add_i32 m0, s11, 0x8000
	v_lshl_add_u64 v[8:9], v[2:3], 0, s[34:35]
	global_load_lds_dwordx4 v[8:9], off
	v_lshl_add_u64 v[2:3], v[2:3], 0, s[36:37]
	s_add_i32 m0, s11, 0xa000
	s_mov_b64 s[36:37], 0x80
	global_load_lds_dwordx4 v[2:3], off
	s_add_i32 m0, s11, 0x10000
	v_lshl_add_u64 v[2:3], v[4:5], 0, s[36:37]
	s_mov_b64 s[36:37], 0x200080
	global_load_lds_dwordx4 v[2:3], off
	v_lshl_add_u64 v[2:3], v[4:5], 0, s[36:37]
	s_add_i32 m0, s11, 0x12000
	v_and_b32_e32 v0, 19, v237
	global_load_lds_dwordx4 v[2:3], off
	v_lshlrev_b32_e32 v2, 1, v237
	v_lshrrev_b32_e32 v35, 1, v34
	v_and_or_b32 v0, v2, 8, v0
	v_and_b32_e32 v22, 4, v35
	v_or_b32_e32 v2, v0, v22
	v_lshl_or_b32 v45, s3, 3, v234
	v_lshlrev_b32_e32 v44, 8, v2
	v_bitop3_b32 v2, v2, v45, 15 bitop3:0x6c
	v_lshl_add_u32 v239, v2, 4, v44
	s_waitcnt vmcnt(6)
	s_barrier
	v_add_u32_e32 v6, 0, v239
	v_bitop3_b32 v0, v0, 15, v22 bitop3:0xc8
	ds_read_b128 v[2:5], v6
	ds_read_b128 v[18:21], v6 offset:8192
	v_bitop3_b32 v22, v45, v0, 2 bitop3:0x36
	v_lshl_add_u32 v240, v22, 4, v44
	v_add_u32_e32 v40, 0, v240
	ds_read_b128 v[36:39], v40
	s_waitcnt vmcnt(0) lgkmcnt(0)
	v_mfma_f32_32x32x16_bf16 v[2:17], v[2:5], v[146:149], 0
	ds_read_b128 v[40:43], v40 offset:8192
	v_bfe_u32 v34, v34, 1, 3
	v_bitop3_b32 v57, v234, v34, 2 bitop3:0x36
	v_bitop3_b32 v58, v234, v34, 4 bitop3:0x36
	v_bitop3_b32 v59, v234, v34, 6 bitop3:0x36
	s_and_b32 s56, s42, 0xfffff000
	s_add_i32 s26, s26, s56
	v_mfma_f32_32x32x16_bf16 v[18:33], v[18:21], v[146:149], 0
	s_lshr_b32 s16, s43, 4
	s_and_b32 s16, s16, 15
	s_lshl_b32 s36, s16, 7
	s_lshl_b32 s37, s16, 8
	s_add_i32 s27, s27, s36
	s_ashr_i32 s57, s56, 31
	s_lshl_b64 s[44:45], s[56:57], 1
	v_mfma_f32_32x32x16_bf16 v[2:17], v[36:39], v[150:153], v[2:17]
	v_bitop3_b32 v36, v45, v0, 4 bitop3:0x36
	v_lshl_add_u32 v241, v36, 4, v44
	v_add_u32_e32 v46, 0, v241
	ds_read_b128 v[36:39], v46
	v_bitop3_b32 v0, v45, v0, 6 bitop3:0x36
	v_lshl_add_u32 v243, v0, 4, v44
	v_add_u32_e32 v0, 0, v243
	s_waitcnt lgkmcnt(1)
	v_mfma_f32_32x32x16_bf16 v[18:33], v[40:43], v[150:153], v[18:33]
	ds_read_b128 v[40:43], v46 offset:8192
	v_lshlrev_b32_e32 v236, 3, v234
	s_mov_b32 s84, s85
	v_bitop3_b32 v56, v35, v234, 7 bitop3:0x6c
	s_mov_b32 s86, s85
	s_mov_b32 s87, s85
	s_mov_b32 s88, s85
	s_waitcnt lgkmcnt(1)
	v_mfma_f32_32x32x16_bf16 v[2:17], v[36:39], v[154:157], v[2:17]
	ds_read_b128 v[36:39], v0
	s_mov_b32 s89, s85
	s_mov_b32 s90, s85
	s_mov_b32 s91, s85
	s_mov_b32 s92, s85
	s_mov_b32 s93, s85
	s_mov_b32 s94, s85
	s_waitcnt lgkmcnt(1)
	v_mfma_f32_32x32x16_bf16 v[18:33], v[40:43], v[154:157], v[18:33]
	ds_read_b128 v[40:43], v0 offset:8192
	s_mov_b32 s95, s85
	s_mov_b32 s96, s85
	s_mov_b32 s97, s85
	s_mov_b32 s98, s85
	s_mov_b32 s99, s85
	s_lshl_b32 s16, s17, 1
	s_waitcnt lgkmcnt(1)
	v_mfma_f32_32x32x16_bf16 v[2:17], v[36:39], v[158:161], v[2:17]
	v_lshlrev_b32_e32 v55, 7, v235
	s_lshr_b32 s19, s20, 6
	s_add_i32 s17, s16, 2
	s_add_i32 s19, s19, 1
	v_lshl_or_b32 v244, v56, 4, v55
	v_lshl_or_b32 v245, v57, 4, v55
	v_lshl_or_b32 v246, v58, 4, v55
	s_waitcnt lgkmcnt(0)
	v_mfma_f32_32x32x16_bf16 v[18:33], v[40:43], v[158:161], v[18:33]
	s_nop 2
	v_max_f32_e32 v34, v3, v3
	v_lshl_or_b32 v247, v59, 4, v55
	s_mov_b32 s23, 1
	v_and_b32_e32 v238, 63, v237
	s_mov_b32 s31, 2
	s_min_u32 s19, s17, s19
	s_addk_i32 s20, 0xff50
	s_nop 1
	v_max_f32_e32 v0, v19, v19
	v_max_f32_e32 v0, v34, v0
	v_max3_f32 v0, v2, v18, v0
	v_max3_f32 v34, v20, v5, v21
	v_max3_f32 v0, v0, v4, v34
	v_max3_f32 v34, v22, v7, v23
	v_max3_f32 v0, v0, v6, v34
	v_max3_f32 v34, v24, v9, v25
	v_max3_f32 v0, v0, v8, v34
	v_max3_f32 v34, v26, v11, v27
	v_max3_f32 v0, v0, v10, v34
	v_max3_f32 v34, v28, v13, v29
	v_max3_f32 v0, v0, v12, v34
	v_max3_f32 v34, v30, v15, v31
	v_max3_f32 v0, v0, v14, v34
	v_max3_f32 v34, v32, v17, v33
	v_max3_f32 v0, v0, v16, v34
	v_mov_b32_e32 v34, v0
	s_nop 1
	v_permlane32_swap_b32_e32 v0, v34
	v_max_f32_e32 v34, v34, v34
	v_max_f32_e32 v0, v0, v0
	v_max_f32_e32 v213, v0, v34
	v_sub_f32_e32 v0, v2, v213
	v_exp_f32_e32 v60, v0
	v_sub_f32_e32 v0, v18, v213
	v_exp_f32_e32 v61, v0
	v_sub_f32_e32 v0, v3, v213
	v_sub_f32_e32 v2, v19, v213
	v_exp_f32_e32 v0, v0
	v_exp_f32_e32 v2, v2
	v_add_f32_e32 v3, v61, v60
	v_mov_b64_e32 v[34:35], s[84:85]
	v_cvt_pk_bf16_f32 v162, v60, v0
	v_pk_add_f32 v[18:19], v[2:3], v[0:1]
	v_sub_f32_e32 v3, v4, v213
	v_sub_f32_e32 v4, v20, v213
	v_pk_add_f32 v[18:19], v[18:19], v[18:19] op_sel_hi:[0,1]
	v_exp_f32_e32 v62, v4
	v_sub_f32_e32 v4, v5, v213
	v_exp_f32_e32 v3, v3
	v_exp_f32_e32 v18, v4
	v_sub_f32_e32 v4, v21, v213
	v_exp_f32_e32 v4, v4
	v_add_f32_e32 v5, v62, v3
	v_sub_u32_e32 v0, 7, v237
	v_cvt_pk_bf16_f32 v178, v61, v2
	v_pk_add_f32 v[20:21], v[4:5], v[18:19]
	v_sub_f32_e32 v5, v6, v213
	v_sub_f32_e32 v6, v22, v213
	v_pk_add_f32 v[20:21], v[20:21], v[20:21] op_sel_hi:[0,1]
	v_exp_f32_e32 v19, v6
	v_sub_f32_e32 v6, v7, v213
	v_exp_f32_e32 v5, v5
	v_exp_f32_e32 v20, v6
	v_sub_f32_e32 v6, v23, v213
	v_exp_f32_e32 v6, v6
	v_add_f32_e32 v7, v19, v5
	v_and_b32_e32 v0, 3, v0
	v_mov_b32_e32 v2, s33
	v_pk_add_f32 v[22:23], v[6:7], v[20:21]
	v_sub_f32_e32 v7, v8, v213
	v_sub_f32_e32 v8, v24, v213
	v_pk_add_f32 v[22:23], v[22:23], v[22:23] op_sel_hi:[0,1]
	v_exp_f32_e32 v21, v8
	v_sub_f32_e32 v8, v9, v213
	v_exp_f32_e32 v7, v7
	v_exp_f32_e32 v22, v8
	v_sub_f32_e32 v8, v25, v213
	v_exp_f32_e32 v8, v8
	v_add_f32_e32 v9, v21, v7
	s_movk_i32 s33, 0x510
	v_mad_u32_u24 v0, v0, s33, v2
	v_pk_add_f32 v[24:25], v[8:9], v[22:23]
	v_sub_f32_e32 v9, v10, v213
	v_sub_f32_e32 v10, v26, v213
	v_pk_add_f32 v[24:25], v[24:25], v[24:25] op_sel_hi:[0,1]
	v_exp_f32_e32 v23, v10
	v_sub_f32_e32 v10, v11, v213
	v_exp_f32_e32 v9, v9
	v_exp_f32_e32 v24, v10
	v_sub_f32_e32 v10, v27, v213
	v_exp_f32_e32 v10, v10
	v_add_f32_e32 v11, v23, v9
	v_or_b32_e32 v2, s26, v233
	v_cvt_pk_bf16_f32 v163, v3, v18
	v_pk_add_f32 v[26:27], v[10:11], v[24:25]
	v_sub_f32_e32 v11, v12, v213
	v_sub_f32_e32 v12, v28, v213
	v_pk_add_f32 v[26:27], v[26:27], v[26:27] op_sel_hi:[0,1]
	v_exp_f32_e32 v25, v12
	v_sub_f32_e32 v12, v13, v213
	v_exp_f32_e32 v11, v11
	v_exp_f32_e32 v26, v12
	v_sub_f32_e32 v12, v29, v213
	v_exp_f32_e32 v12, v12
	v_add_f32_e32 v13, v25, v11
	v_ashrrev_i32_e32 v3, 31, v2
	v_lshlrev_b64 v[214:215], 12, v[2:3]
	v_pk_add_f32 v[28:29], v[12:13], v[26:27]
	v_sub_f32_e32 v13, v14, v213
	v_sub_f32_e32 v14, v30, v213
	v_pk_add_f32 v[28:29], v[28:29], v[28:29] op_sel_hi:[0,1]
	v_exp_f32_e32 v27, v14
	v_sub_f32_e32 v14, v15, v213
	v_exp_f32_e32 v13, v13
	v_exp_f32_e32 v28, v14
	v_sub_f32_e32 v14, v31, v213
	v_exp_f32_e32 v14, v14
	v_sub_f32_e32 v15, v16, v213
	v_exp_f32_e32 v63, v15
	v_sub_f32_e32 v15, v32, v213
	v_exp_f32_e32 v32, v15
	v_add_f32_e32 v15, v27, v13
	v_pk_add_f32 v[30:31], v[14:15], v[28:29]
	v_bitop3_b32 v2, v52, 15, v237 bitop3:0x48
	v_pk_add_f32 v[30:31], v[30:31], v[30:31] op_sel_hi:[0,1]
	v_sub_f32_e32 v15, v17, v213
	v_lshlrev_b32_e32 v2, 4, v2
	v_exp_f32_e32 v30, v15
	v_sub_f32_e32 v15, v33, v213
	v_or3_b32 v214, v214, s37, v2
	v_or_b32_e32 v2, s27, v53
	v_exp_f32_e32 v50, v15
	v_ashrrev_i32_e32 v3, 31, v2
	v_cvt_pk_bf16_f32 v179, v62, v4
	v_lshlrev_b64 v[2:3], 15, v[2:3]
	v_bitop3_b32 v4, v54, 7, v237 bitop3:0x48
	v_lshl_or_b32 v2, v4, 4, v2
	v_add_f32_e32 v51, v32, v63
	v_lshl_add_u64 v[216:217], v[2:3], 0, s[44:45]
	v_sub_u32_e32 v2, v236, v235
	v_mov_b64_e32 v[48:49], s[98:99]
	v_pk_add_f32 v[16:17], v[50:51], v[30:31]
	v_subrev_u32_e32 v2, s22, v2
	v_mov_b64_e32 v[36:37], s[86:87]
	v_mov_b64_e32 v[38:39], s[88:89]
	v_mov_b64_e32 v[40:41], s[90:91]
	v_mov_b64_e32 v[42:43], s[92:93]
	v_mov_b64_e32 v[44:45], s[94:95]
	v_mov_b64_e32 v[46:47], s[96:97]
	v_xor_b32_e32 v66, 0x80000000, v213
	v_add_f32_e32 v242, v16, v17
	v_cvt_pk_bf16_f32 v164, v5, v20
	v_cvt_pk_bf16_f32 v165, v7, v22
	v_cvt_pk_bf16_f32 v170, v9, v24
	v_cvt_pk_bf16_f32 v171, v11, v26
	v_cvt_pk_bf16_f32 v172, v13, v28
	v_cvt_pk_bf16_f32 v173, v63, v30
	v_cvt_pk_bf16_f32 v180, v19, v6
	v_cvt_pk_bf16_f32 v181, v21, v8
	v_cvt_pk_bf16_f32 v186, v23, v10
	v_cvt_pk_bf16_f32 v187, v25, v12
	v_cvt_pk_bf16_f32 v188, v27, v14
	v_cvt_pk_bf16_f32 v189, v32, v50
	v_subrev_u32_e32 v248, s21, v2
	v_mov_b64_e32 v[64:65], v[48:49]
	v_mov_b64_e32 v[18:19], v[34:35]
	v_mov_b64_e32 v[2:3], v[34:35]
	v_readlane_b32 s94, v255, 10
	v_readlane_b32 s90, v255, 12
	v_mov_b32_e32 v67, v66
	v_mov_b32_e32 v68, v66
	v_mov_b32_e32 v69, v66
	v_mov_b32_e32 v70, v66
	v_mov_b32_e32 v71, v66
	v_mov_b32_e32 v72, v66
	v_mov_b32_e32 v73, v66
	v_mov_b32_e32 v74, v66
	v_mov_b32_e32 v75, v66
	v_mov_b32_e32 v76, v66
	v_mov_b32_e32 v77, v66
	v_mov_b32_e32 v78, v66
	v_mov_b32_e32 v79, v66
	v_mov_b32_e32 v80, v66
	v_mov_b32_e32 v81, v66
	s_mov_b32 s21, 0
	v_mov_b32_e32 v166, 0
	v_mov_b32_e32 v167, 0
	v_mov_b32_e32 v168, 0
	v_mov_b32_e32 v169, 0
	v_mov_b32_e32 v174, 0
	v_mov_b32_e32 v175, 0
	v_mov_b32_e32 v176, 0
	v_mov_b32_e32 v177, 0
	v_mov_b32_e32 v182, 0
	v_mov_b32_e32 v183, 0
	v_mov_b32_e32 v184, 0
	v_mov_b32_e32 v185, 0
	v_mov_b32_e32 v190, 0
	v_mov_b32_e32 v191, 0
	v_mov_b32_e32 v192, 0
	v_mov_b32_e32 v193, 0
	v_mov_b64_e32 v[62:63], v[46:47]
	v_mov_b64_e32 v[60:61], v[44:45]
	v_mov_b64_e32 v[58:59], v[42:43]
	v_mov_b64_e32 v[56:57], v[40:41]
	v_mov_b64_e32 v[54:55], v[38:39]
	v_mov_b64_e32 v[52:53], v[36:37]
	v_mov_b64_e32 v[50:51], v[34:35]
	v_mov_b64_e32 v[20:21], v[36:37]
	v_mov_b64_e32 v[22:23], v[38:39]
	v_mov_b64_e32 v[24:25], v[40:41]
	v_mov_b64_e32 v[26:27], v[42:43]
	v_mov_b64_e32 v[28:29], v[44:45]
	v_mov_b64_e32 v[30:31], v[46:47]
	v_mov_b64_e32 v[32:33], v[48:49]
	v_mov_b64_e32 v[4:5], v[36:37]
	v_mov_b64_e32 v[6:7], v[38:39]
	v_mov_b64_e32 v[8:9], v[40:41]
	v_mov_b64_e32 v[10:11], v[42:43]
	v_mov_b64_e32 v[12:13], v[44:45]
	v_mov_b64_e32 v[14:15], v[46:47]
	v_mov_b64_e32 v[16:17], v[48:49]
	s_mov_b32 s33, 1
	s_mov_b32 s48, 0
	s_mov_b32 s49, 0
	s_movk_i32 s92, 0x6e
	s_movk_i32 s93, 0xd0
	s_mov_b32 s57, 0x41000000
	v_readlane_b32 s95, v255, 11
	v_readlane_b32 s91, v255, 13
	s_mov_b64 s[62:63], 0xd0e0000
	s_mov_b64 s[96:97], 0x15000100

.LBB0_248:
	v_readlane_b32 s2, v252, 10
	s_barrier
	v_mbcnt_lo_u32_b32 v237, -1, 0
	v_mbcnt_hi_u32_b32 v237, -1, v237
	s_nop 0
	v_add_u32_e32 v2, s2, v237
	s_movk_i32 s2, 0x80
	v_readfirstlane_b32 s3, v2
	v_cmp_gt_i32_e32 vcc, s2, v2
	s_branch .Ltb_u2_a
	s_and_saveexec_b64 s[26:27], vcc
	s_cbranch_execz .LBB0_250
	v_readlane_b32 s10, v255, 39
	v_ashrrev_i32_e32 v3, 31, v2
	v_readlane_b32 s11, v255, 40
	v_lshl_add_u32 v0, v2, 2, 0
	v_add_u32_e32 v0, 0x19000, v0
	v_lshl_add_u64 v[4:5], v[2:3], 2, s[10:11]
	global_load_dword v3, v[4:5], off
	s_waitcnt vmcnt(0)
	ds_write_b32 v0, v3

.Ltb_u2_a:
	s_movk_i32 s2, 0x510
	v_cmp_gt_i32_e32 vcc, s2, v2
	s_branch .Ltb_u2_b
	s_and_saveexec_b64 s[26:27], vcc
	s_cbranch_execz .LBB0_259
	global_load_dword v3, v1, s[38:39] offset:1984
	v_sub_u32_e32 v4, 0xdf, v2
	v_lshl_add_u32 v5, v2, 2, s31
	s_mov_b64 s[38:39], 0
	v_mov_b32_e32 v6, v2
	s_branch .LBB0_255

.Ltb_u2_b:
	s_ashr_i32 s2, s3, 6
	s_lshl_b32 s20, s2, 2
	v_bfe_u32 v233, v237, 4, 2
	v_or_b32_e32 v0, s20, v233
	v_add_u32_e32 v4, s60, v0
	v_ashrrev_i32_e32 v5, 31, v4
	v_readlane_b32 s10, v252, 31
	v_bitop3_b32 v34, s20, v237, v233 bitop3:0x36
	v_lshlrev_b64 v[4:5], 12, v[4:5]
	v_readlane_b32 s11, v252, 32
	s_lshl_b32 s84, s18, 1
	v_lshlrev_b32_e32 v0, 4, v34
	v_lshl_add_u64 v[4:5], s[10:11], 0, v[4:5]
	v_lshl_add_u64 v[4:5], v[4:5], 0, s[84:85]
	v_and_b32_e32 v0, 0xf0, v0
	s_lshl_b32 s21, s2, 3
	v_bfe_u32 v36, v237, 3, 3
	v_lshl_add_u64 v[6:7], v[4:5], 0, v[0:1]
	v_or_b32_e32 v0, s21, v36
	v_add_u32_e32 v4, s18, v0
	s_lshl_b32 s6, s2, 10
	s_mov_b64 s[16:17], 0x20000
	v_ashrrev_i32_e32 v5, 31, v4
	s_add_i32 s10, s6, 0
	v_lshl_add_u64 v[8:9], v[6:7], 0, s[16:17]
	v_readlane_b32 s16, v252, 39
	s_waitcnt vmcnt(0)
	v_lshrrev_b32_e32 v3, 1, v0
	v_lshlrev_b64 v[4:5], 15, v[4:5]
	s_mov_b32 m0, s10
	v_readlane_b32 s17, v252, 40
	v_xor_b32_e32 v35, v3, v237
	global_load_lds_dwordx4 v[6:7], off
	s_add_i32 m0, s10, 0x2000
	v_lshl_add_u64 v[4:5], s[16:17], 0, v[4:5]
	s_mov_b64 s[16:17], 0x40000
	global_load_lds_dwordx4 v[8:9], off
	s_add_i32 m0, s10, 0x4000
	v_lshl_add_u64 v[8:9], v[6:7], 0, s[16:17]
	s_mov_b64 s[16:17], 0x60000
	v_lshlrev_b32_e32 v0, 4, v35
	v_lshl_add_u64 v[4:5], s[60:61], 1, v[4:5]
	global_load_lds_dwordx4 v[8:9], off
	v_lshl_add_u64 v[8:9], v[6:7], 0, s[16:17]
	s_add_i32 m0, s10, 0x6000
	v_and_b32_e32 v0, 0x70, v0
	global_load_lds_dwordx4 v[8:9], off
	v_lshl_add_u64 v[4:5], v[4:5], 0, v[0:1]
	s_add_i32 m0, s10, 0xc000
	s_mov_b64 s[16:17], 0x200000
	global_load_lds_dwordx4 v[4:5], off
	v_lshl_add_u64 v[8:9], v[4:5], 0, s[16:17]
	s_add_i32 m0, s10, 0xe000
	s_cmp_lg_u32 s46, 0
	global_load_lds_dwordx4 v[8:9], off
	s_cbranch_scc0 .LBB0_261
	s_mov_b64 s[16:17], 0xa0000
	s_add_i32 m0, s10, 0x8000
	s_add_i32 s6, s10, 0xa000
	v_lshl_add_u64 v[8:9], v[6:7], 0, s[16:17]
	v_lshl_add_u64 v[6:7], v[6:7], 0, s[34:35]
	global_load_lds_dwordx4 v[6:7], off
	s_mov_b32 m0, s6
	s_nop 0
	global_load_lds_dwordx4 v[8:9], off
